# G2 EpiRes epilogue fast path for bf16 residual: 16 residual loads in flight with counted vmcnt, then add/cvt/store (was 16x serialized load-wait-store)
# speedup vs baseline: 1.0002x; 1.0002x over previous
; __device__ __forceinline__ unsigned cvt_pk_bf16(float lo, float hi) { unsigned r; asm volatile("v_cvt_pk_bf16_f32 %0, %1, %2" : "=v"(r) : "v"(lo), "v"(hi)); return r; }
;     __device__ __forceinline__ void operator()(const f32x4 (&acc)[2][2][4][2], const Unit& u, int wr, int wc, int fr, int fq) const {
;     ...
;             for (int m = 0; m < 4; ++m) { const size_t off = (size_t)(row0 + ai * HALF + m * 16) * ldc + col0;
; #pragma unroll
;                 for (int bj = 0; bj < 2; ++bj) { const size_t o = off + bj * HALF; f32x4 v0 = acc[ai][bj][m][0], v1 = acc[ai][bj][m][1];
;                     if (xin32) { v0 += *(const f32x4*)(xin32 + o); v1 += *(const f32x4*)(xin32 + o + 4); }
;                     else { const u32x4 rb = *(const u32x4*)(xinb + o);
;                         v0 += (f32x4){__uint_as_float(rb.x << 16), __uint_as_float(rb.x & 0xffff0000u), __uint_as_float(rb.y << 16), __uint_as_float(rb.y & 0xffff0000u)};
;                         v1 += (f32x4){__uint_as_float(rb.z << 16), __uint_as_float(rb.z & 0xffff0000u), __uint_as_float(rb.w << 16), __uint_as_float(rb.w & 0xffff0000u)}; }
;                     if (xout32) { *(f32x4*)(xout32 + o) = v0; *(f32x4*)(xout32 + o + 4) = v1; }
;                     else { u32x4 w; w.x = cvt_pk_bf16(v0[0], v0[1]); w.y = cvt_pk_bf16(v0[2], v0[3]); w.z = cvt_pk_bf16(v1[0], v1[1]); w.w = cvt_pk_bf16(v1[2], v1[3]); *(u32x4*)(xbo + o) = w; } } }
.Lg2_fast:
	v_lshlrev_b32_e32 v156, 1, v152
	v_lshlrev_b32_e32 v157, 2, v152
	s_mov_b64 s[2:3], s[36:37]
	global_load_dwordx4 v[162:165], v156, s[2:3]
	global_load_dwordx4 v[166:169], v156, s[2:3] offset:256
	s_add_u32 s2, s2, 0x8000
	s_addc_u32 s3, s3, 0
	global_load_dwordx4 v[170:173], v156, s[2:3]
	global_load_dwordx4 v[174:177], v156, s[2:3] offset:256
	s_add_u32 s2, s2, 0x8000
	s_addc_u32 s3, s3, 0
	global_load_dwordx4 v[178:181], v156, s[2:3]
	global_load_dwordx4 v[182:185], v156, s[2:3] offset:256
	s_add_u32 s2, s2, 0x8000
	s_addc_u32 s3, s3, 0
	global_load_dwordx4 v[202:205], v156, s[2:3]
	global_load_dwordx4 v[214:217], v156, s[2:3] offset:256
	s_add_u32 s2, s2, 0x28000
	s_addc_u32 s3, s3, 0
	global_load_dwordx4 v[218:221], v156, s[2:3]
	global_load_dwordx4 v[222:225], v156, s[2:3] offset:256
	s_add_u32 s2, s2, 0x8000
	s_addc_u32 s3, s3, 0
	global_load_dwordx4 v[226:229], v156, s[2:3]
	global_load_dwordx4 v[230:233], v156, s[2:3] offset:256
	s_add_u32 s2, s2, 0x8000
	s_addc_u32 s3, s3, 0
	global_load_dwordx4 v[130:133], v156, s[2:3]
	global_load_dwordx4 v[134:137], v156, s[2:3] offset:256
	s_add_u32 s2, s2, 0x8000
	s_addc_u32 s3, s3, 0
	global_load_dwordx4 v[234:237], v156, s[2:3]
	global_load_dwordx4 v[242:245], v156, s[2:3] offset:256
	s_and_b64 vcc, exec, s[22:23]
	s_cbranch_vccnz .Lg2_fast_f32
	s_mov_b64 s[2:3], s[36:37]
	s_waitcnt vmcnt(15)
	v_lshlrev_b32_e32 v148, 16, v162
	v_lshlrev_b32_e32 v149, 16, v163
	v_lshlrev_b32_e32 v150, 16, v164
	v_lshlrev_b32_e32 v151, 16, v165
	v_and_b32_e32 v162, 0xffff0000, v162
	v_and_b32_e32 v163, 0xffff0000, v163
	v_and_b32_e32 v164, 0xffff0000, v164
	v_and_b32_e32 v165, 0xffff0000, v165
	v_add_f32_e32 v122, v122, v148
	v_add_f32_e32 v123, v123, v162
	v_add_f32_e32 v124, v124, v149
	v_add_f32_e32 v125, v125, v163
	v_add_f32_e32 v126, v126, v150
	v_add_f32_e32 v127, v127, v164
	v_add_f32_e32 v128, v128, v151
	v_add_f32_e32 v129, v129, v165
	v_cvt_pk_bf16_f32 v122, v122, v123
	v_cvt_pk_bf16_f32 v123, v124, v125
	v_cvt_pk_bf16_f32 v124, v126, v127
	v_cvt_pk_bf16_f32 v125, v128, v129
	global_store_dwordx4 v156, v[122:125], s[2:3]
	s_waitcnt vmcnt(15)
	v_lshlrev_b32_e32 v152, 16, v166
	v_lshlrev_b32_e32 v153, 16, v167
	v_lshlrev_b32_e32 v154, 16, v168
	v_lshlrev_b32_e32 v155, 16, v169
	v_and_b32_e32 v166, 0xffff0000, v166
	v_and_b32_e32 v167, 0xffff0000, v167
	v_and_b32_e32 v168, 0xffff0000, v168
	v_and_b32_e32 v169, 0xffff0000, v169
	v_add_f32_e32 v114, v114, v152
	v_add_f32_e32 v115, v115, v166
	v_add_f32_e32 v116, v116, v153
	v_add_f32_e32 v117, v117, v167
	v_add_f32_e32 v118, v118, v154
	v_add_f32_e32 v119, v119, v168
	v_add_f32_e32 v120, v120, v155
	v_add_f32_e32 v121, v121, v169
	v_cvt_pk_bf16_f32 v114, v114, v115
	v_cvt_pk_bf16_f32 v115, v116, v117
	v_cvt_pk_bf16_f32 v116, v118, v119
	v_cvt_pk_bf16_f32 v117, v120, v121
	global_store_dwordx4 v156, v[114:117], s[2:3] offset:256
	s_add_u32 s2, s2, 0x8000
	s_addc_u32 s3, s3, 0
	s_waitcnt vmcnt(15)
	v_lshlrev_b32_e32 v148, 16, v170
	v_lshlrev_b32_e32 v149, 16, v171
	v_lshlrev_b32_e32 v150, 16, v172
	v_lshlrev_b32_e32 v151, 16, v173
	v_and_b32_e32 v170, 0xffff0000, v170
	v_and_b32_e32 v171, 0xffff0000, v171
	v_and_b32_e32 v172, 0xffff0000, v172
	v_and_b32_e32 v173, 0xffff0000, v173
	v_add_f32_e32 v106, v106, v148
	v_add_f32_e32 v107, v107, v170
	v_add_f32_e32 v108, v108, v149
	v_add_f32_e32 v109, v109, v171
	v_add_f32_e32 v110, v110, v150
	v_add_f32_e32 v111, v111, v172
	v_add_f32_e32 v112, v112, v151
	v_add_f32_e32 v113, v113, v173
	v_cvt_pk_bf16_f32 v106, v106, v107
	v_cvt_pk_bf16_f32 v107, v108, v109
	v_cvt_pk_bf16_f32 v108, v110, v111
	v_cvt_pk_bf16_f32 v109, v112, v113
	global_store_dwordx4 v156, v[106:109], s[2:3]
	s_waitcnt vmcnt(15)
	v_lshlrev_b32_e32 v152, 16, v174
	v_lshlrev_b32_e32 v153, 16, v175
	v_lshlrev_b32_e32 v154, 16, v176
	v_lshlrev_b32_e32 v155, 16, v177
	v_and_b32_e32 v174, 0xffff0000, v174
	v_and_b32_e32 v175, 0xffff0000, v175
	v_and_b32_e32 v176, 0xffff0000, v176
	v_and_b32_e32 v177, 0xffff0000, v177
	v_add_f32_e32 v98, v98, v152
	v_add_f32_e32 v99, v99, v174
	v_add_f32_e32 v100, v100, v153
	v_add_f32_e32 v101, v101, v175
	v_add_f32_e32 v102, v102, v154
	v_add_f32_e32 v103, v103, v176
	v_add_f32_e32 v104, v104, v155
	v_add_f32_e32 v105, v105, v177
	v_cvt_pk_bf16_f32 v98, v98, v99
	v_cvt_pk_bf16_f32 v99, v100, v101
	v_cvt_pk_bf16_f32 v100, v102, v103
	v_cvt_pk_bf16_f32 v101, v104, v105
	global_store_dwordx4 v156, v[98:101], s[2:3] offset:256
	s_add_u32 s2, s2, 0x8000
	s_addc_u32 s3, s3, 0
	s_waitcnt vmcnt(15)
	v_lshlrev_b32_e32 v148, 16, v178
	v_lshlrev_b32_e32 v149, 16, v179
	v_lshlrev_b32_e32 v150, 16, v180
	v_lshlrev_b32_e32 v151, 16, v181
	v_and_b32_e32 v178, 0xffff0000, v178
	v_and_b32_e32 v179, 0xffff0000, v179
	v_and_b32_e32 v180, 0xffff0000, v180
	v_and_b32_e32 v181, 0xffff0000, v181
	v_add_f32_e32 v90, v90, v148
	v_add_f32_e32 v91, v91, v178
	v_add_f32_e32 v92, v92, v149
	v_add_f32_e32 v93, v93, v179
	v_add_f32_e32 v94, v94, v150
	v_add_f32_e32 v95, v95, v180
	v_add_f32_e32 v96, v96, v151
	v_add_f32_e32 v97, v97, v181
	v_cvt_pk_bf16_f32 v90, v90, v91
	v_cvt_pk_bf16_f32 v91, v92, v93
	v_cvt_pk_bf16_f32 v92, v94, v95
	v_cvt_pk_bf16_f32 v93, v96, v97
	global_store_dwordx4 v156, v[90:93], s[2:3]
	s_waitcnt vmcnt(15)
	v_lshlrev_b32_e32 v152, 16, v182
	v_lshlrev_b32_e32 v153, 16, v183
	v_lshlrev_b32_e32 v154, 16, v184
	v_lshlrev_b32_e32 v155, 16, v185
	v_and_b32_e32 v182, 0xffff0000, v182
	v_and_b32_e32 v183, 0xffff0000, v183
	v_and_b32_e32 v184, 0xffff0000, v184
	v_and_b32_e32 v185, 0xffff0000, v185
	v_add_f32_e32 v82, v82, v152
	v_add_f32_e32 v83, v83, v182
	v_add_f32_e32 v84, v84, v153
	v_add_f32_e32 v85, v85, v183
	v_add_f32_e32 v86, v86, v154
	v_add_f32_e32 v87, v87, v184
	v_add_f32_e32 v88, v88, v155
	v_add_f32_e32 v89, v89, v185
	v_cvt_pk_bf16_f32 v82, v82, v83
	v_cvt_pk_bf16_f32 v83, v84, v85
	v_cvt_pk_bf16_f32 v84, v86, v87
	v_cvt_pk_bf16_f32 v85, v88, v89
	global_store_dwordx4 v156, v[82:85], s[2:3] offset:256
	s_add_u32 s2, s2, 0x8000
	s_addc_u32 s3, s3, 0
	s_waitcnt vmcnt(15)
; __device__ __forceinline__ unsigned cvt_pk_bf16(float lo, float hi) { unsigned r; asm volatile("v_cvt_pk_bf16_f32 %0, %1, %2" : "=v"(r) : "v"(lo), "v"(hi)); return r; }
;     __device__ __forceinline__ void operator()(const f32x4 (&acc)[2][2][4][2], const Unit& u, int wr, int wc, int fr, int fq) const {
;     ...
;             for (int m = 0; m < 4; ++m) { const size_t off = (size_t)(row0 + ai * HALF + m * 16) * ldc + col0;
; #pragma unroll
;                 for (int bj = 0; bj < 2; ++bj) { const size_t o = off + bj * HALF; f32x4 v0 = acc[ai][bj][m][0], v1 = acc[ai][bj][m][1];
;                     if (xin32) { v0 += *(const f32x4*)(xin32 + o); v1 += *(const f32x4*)(xin32 + o + 4); }
;                     else { const u32x4 rb = *(const u32x4*)(xinb + o);
;                         v0 += (f32x4){__uint_as_float(rb.x << 16), __uint_as_float(rb.x & 0xffff0000u), __uint_as_float(rb.y << 16), __uint_as_float(rb.y & 0xffff0000u)};
;                         v1 += (f32x4){__uint_as_float(rb.z << 16), __uint_as_float(rb.z & 0xffff0000u), __uint_as_float(rb.w << 16), __uint_as_float(rb.w & 0xffff0000u)}; }
;                     if (xout32) { *(f32x4*)(xout32 + o) = v0; *(f32x4*)(xout32 + o + 4) = v1; }
;                     else { u32x4 w; w.x = cvt_pk_bf16(v0[0], v0[1]); w.y = cvt_pk_bf16(v0[2], v0[3]); w.z = cvt_pk_bf16(v1[0], v1[1]); w.w = cvt_pk_bf16(v1[2], v1[3]); *(u32x4*)(xbo + o) = w; } } }
	v_lshlrev_b32_e32 v148, 16, v202
	v_lshlrev_b32_e32 v149, 16, v203
	v_lshlrev_b32_e32 v150, 16, v204
	v_lshlrev_b32_e32 v151, 16, v205
	v_and_b32_e32 v202, 0xffff0000, v202
	v_and_b32_e32 v203, 0xffff0000, v203
	v_and_b32_e32 v204, 0xffff0000, v204
	v_and_b32_e32 v205, 0xffff0000, v205
	v_add_f32_e32 v74, v74, v148
	v_add_f32_e32 v75, v75, v202
	v_add_f32_e32 v76, v76, v149
	v_add_f32_e32 v77, v77, v203
	v_add_f32_e32 v78, v78, v150
	v_add_f32_e32 v79, v79, v204
	v_add_f32_e32 v80, v80, v151
	v_add_f32_e32 v81, v81, v205
	v_cvt_pk_bf16_f32 v74, v74, v75
	v_cvt_pk_bf16_f32 v75, v76, v77
	v_cvt_pk_bf16_f32 v76, v78, v79
	v_cvt_pk_bf16_f32 v77, v80, v81
	global_store_dwordx4 v156, v[74:77], s[2:3]
	s_waitcnt vmcnt(15)
	v_lshlrev_b32_e32 v152, 16, v214
	v_lshlrev_b32_e32 v153, 16, v215
	v_lshlrev_b32_e32 v154, 16, v216
	v_lshlrev_b32_e32 v155, 16, v217
	v_and_b32_e32 v214, 0xffff0000, v214
	v_and_b32_e32 v215, 0xffff0000, v215
	v_and_b32_e32 v216, 0xffff0000, v216
	v_and_b32_e32 v217, 0xffff0000, v217
	v_add_f32_e32 v66, v66, v152
	v_add_f32_e32 v67, v67, v214
	v_add_f32_e32 v68, v68, v153
	v_add_f32_e32 v69, v69, v215
	v_add_f32_e32 v70, v70, v154
	v_add_f32_e32 v71, v71, v216
	v_add_f32_e32 v72, v72, v155
	v_add_f32_e32 v73, v73, v217
	v_cvt_pk_bf16_f32 v66, v66, v67
	v_cvt_pk_bf16_f32 v67, v68, v69
	v_cvt_pk_bf16_f32 v68, v70, v71
	v_cvt_pk_bf16_f32 v69, v72, v73
	global_store_dwordx4 v156, v[66:69], s[2:3] offset:256
	s_add_u32 s2, s2, 0x28000
	s_addc_u32 s3, s3, 0
	s_waitcnt vmcnt(15)
	v_lshlrev_b32_e32 v148, 16, v218
	v_lshlrev_b32_e32 v149, 16, v219
	v_lshlrev_b32_e32 v150, 16, v220
	v_lshlrev_b32_e32 v151, 16, v221
	v_and_b32_e32 v218, 0xffff0000, v218
	v_and_b32_e32 v219, 0xffff0000, v219
	v_and_b32_e32 v220, 0xffff0000, v220
	v_and_b32_e32 v221, 0xffff0000, v221
	v_add_f32_e32 v58, v58, v148
	v_add_f32_e32 v59, v59, v218
	v_add_f32_e32 v60, v60, v149
	v_add_f32_e32 v61, v61, v219
	v_add_f32_e32 v62, v62, v150
	v_add_f32_e32 v63, v63, v220
	v_add_f32_e32 v64, v64, v151
	v_add_f32_e32 v65, v65, v221
	v_cvt_pk_bf16_f32 v58, v58, v59
	v_cvt_pk_bf16_f32 v59, v60, v61
	v_cvt_pk_bf16_f32 v60, v62, v63
	v_cvt_pk_bf16_f32 v61, v64, v65
	global_store_dwordx4 v156, v[58:61], s[2:3]
	s_waitcnt vmcnt(15)
	v_lshlrev_b32_e32 v152, 16, v222
	v_lshlrev_b32_e32 v153, 16, v223
	v_lshlrev_b32_e32 v154, 16, v224
	v_lshlrev_b32_e32 v155, 16, v225
	v_and_b32_e32 v222, 0xffff0000, v222
	v_and_b32_e32 v223, 0xffff0000, v223
	v_and_b32_e32 v224, 0xffff0000, v224
	v_and_b32_e32 v225, 0xffff0000, v225
	v_add_f32_e32 v50, v50, v152
	v_add_f32_e32 v51, v51, v222
	v_add_f32_e32 v52, v52, v153
	v_add_f32_e32 v53, v53, v223
	v_add_f32_e32 v54, v54, v154
	v_add_f32_e32 v55, v55, v224
	v_add_f32_e32 v56, v56, v155
	v_add_f32_e32 v57, v57, v225
	v_cvt_pk_bf16_f32 v50, v50, v51
	v_cvt_pk_bf16_f32 v51, v52, v53
	v_cvt_pk_bf16_f32 v52, v54, v55
	v_cvt_pk_bf16_f32 v53, v56, v57
	global_store_dwordx4 v156, v[50:53], s[2:3] offset:256
	s_add_u32 s2, s2, 0x8000
	s_addc_u32 s3, s3, 0
	s_waitcnt vmcnt(15)
	v_lshlrev_b32_e32 v148, 16, v226
	v_lshlrev_b32_e32 v149, 16, v227
	v_lshlrev_b32_e32 v150, 16, v228
	v_lshlrev_b32_e32 v151, 16, v229
	v_and_b32_e32 v226, 0xffff0000, v226
	v_and_b32_e32 v227, 0xffff0000, v227
	v_and_b32_e32 v228, 0xffff0000, v228
	v_and_b32_e32 v229, 0xffff0000, v229
	v_add_f32_e32 v42, v42, v148
	v_add_f32_e32 v43, v43, v226
	v_add_f32_e32 v44, v44, v149
	v_add_f32_e32 v45, v45, v227
	v_add_f32_e32 v46, v46, v150
	v_add_f32_e32 v47, v47, v228
	v_add_f32_e32 v48, v48, v151
	v_add_f32_e32 v49, v49, v229
	v_cvt_pk_bf16_f32 v42, v42, v43
	v_cvt_pk_bf16_f32 v43, v44, v45
	v_cvt_pk_bf16_f32 v44, v46, v47
	v_cvt_pk_bf16_f32 v45, v48, v49
	global_store_dwordx4 v156, v[42:45], s[2:3]
	s_waitcnt vmcnt(15)
	v_lshlrev_b32_e32 v152, 16, v230
	v_lshlrev_b32_e32 v153, 16, v231
	v_lshlrev_b32_e32 v154, 16, v232
	v_lshlrev_b32_e32 v155, 16, v233
	v_and_b32_e32 v230, 0xffff0000, v230
	v_and_b32_e32 v231, 0xffff0000, v231
	v_and_b32_e32 v232, 0xffff0000, v232
	v_and_b32_e32 v233, 0xffff0000, v233
	v_add_f32_e32 v34, v34, v152
	v_add_f32_e32 v35, v35, v230
	v_add_f32_e32 v36, v36, v153
	v_add_f32_e32 v37, v37, v231
	v_add_f32_e32 v38, v38, v154
	v_add_f32_e32 v39, v39, v232
	v_add_f32_e32 v40, v40, v155
	v_add_f32_e32 v41, v41, v233
	v_cvt_pk_bf16_f32 v34, v34, v35
	v_cvt_pk_bf16_f32 v35, v36, v37
	v_cvt_pk_bf16_f32 v36, v38, v39
	v_cvt_pk_bf16_f32 v37, v40, v41
	global_store_dwordx4 v156, v[34:37], s[2:3] offset:256
	s_add_u32 s2, s2, 0x8000
	s_addc_u32 s3, s3, 0
	s_waitcnt vmcnt(15)
	v_lshlrev_b32_e32 v148, 16, v130
	v_lshlrev_b32_e32 v149, 16, v131
	v_lshlrev_b32_e32 v150, 16, v132
	v_lshlrev_b32_e32 v151, 16, v133
	v_and_b32_e32 v130, 0xffff0000, v130
	v_and_b32_e32 v131, 0xffff0000, v131
	v_and_b32_e32 v132, 0xffff0000, v132
	v_and_b32_e32 v133, 0xffff0000, v133
	v_add_f32_e32 v26, v26, v148
	v_add_f32_e32 v27, v27, v130
	v_add_f32_e32 v28, v28, v149
	v_add_f32_e32 v29, v29, v131
	v_add_f32_e32 v30, v30, v150
	v_add_f32_e32 v31, v31, v132
	v_add_f32_e32 v32, v32, v151
	v_add_f32_e32 v33, v33, v133
	v_cvt_pk_bf16_f32 v26, v26, v27
	v_cvt_pk_bf16_f32 v27, v28, v29
	v_cvt_pk_bf16_f32 v28, v30, v31
	v_cvt_pk_bf16_f32 v29, v32, v33
	global_store_dwordx4 v156, v[26:29], s[2:3]
	s_waitcnt vmcnt(15)
;     __device__ __forceinline__ void operator()(const f32x4 (&acc)[2][2][4][2], const Unit& u, int wr, int wc, int fr, int fq) const {
;     ...
;             for (int m = 0; m < 4; ++m) { const size_t off = (size_t)(row0 + ai * HALF + m * 16) * ldc + col0;
; #pragma unroll
;                 for (int bj = 0; bj < 2; ++bj) { const size_t o = off + bj * HALF; f32x4 v0 = acc[ai][bj][m][0], v1 = acc[ai][bj][m][1];
;                     if (xin32) { v0 += *(const f32x4*)(xin32 + o); v1 += *(const f32x4*)(xin32 + o + 4); }
;                     else { const u32x4 rb = *(const u32x4*)(xinb + o);
;                         v0 += (f32x4){__uint_as_float(rb.x << 16), __uint_as_float(rb.x & 0xffff0000u), __uint_as_float(rb.y << 16), __uint_as_float(rb.y & 0xffff0000u)};
;                         v1 += (f32x4){__uint_as_float(rb.z << 16), __uint_as_float(rb.z & 0xffff0000u), __uint_as_float(rb.w << 16), __uint_as_float(rb.w & 0xffff0000u)}; }
;                     if (xout32) { *(f32x4*)(xout32 + o) = v0; *(f32x4*)(xout32 + o + 4) = v1; }
	v_lshlrev_b32_e32 v152, 16, v134
	v_lshlrev_b32_e32 v153, 16, v135
	v_lshlrev_b32_e32 v154, 16, v136
	v_lshlrev_b32_e32 v155, 16, v137
	v_and_b32_e32 v134, 0xffff0000, v134
	v_and_b32_e32 v135, 0xffff0000, v135
	v_and_b32_e32 v136, 0xffff0000, v136
	v_and_b32_e32 v137, 0xffff0000, v137
	v_add_f32_e32 v18, v18, v152
	v_add_f32_e32 v19, v19, v134
	v_add_f32_e32 v20, v20, v153
	v_add_f32_e32 v21, v21, v135
	v_add_f32_e32 v22, v22, v154
	v_add_f32_e32 v23, v23, v136
	v_add_f32_e32 v24, v24, v155
	v_add_f32_e32 v25, v25, v137
	v_cvt_pk_bf16_f32 v18, v18, v19
	v_cvt_pk_bf16_f32 v19, v20, v21
	v_cvt_pk_bf16_f32 v20, v22, v23
	v_cvt_pk_bf16_f32 v21, v24, v25
	global_store_dwordx4 v156, v[18:21], s[2:3] offset:256
	s_add_u32 s2, s2, 0x8000
	s_addc_u32 s3, s3, 0
	s_waitcnt vmcnt(15)
	v_lshlrev_b32_e32 v148, 16, v234
	v_lshlrev_b32_e32 v149, 16, v235
	v_lshlrev_b32_e32 v150, 16, v236
	v_lshlrev_b32_e32 v151, 16, v237
	v_and_b32_e32 v234, 0xffff0000, v234
	v_and_b32_e32 v235, 0xffff0000, v235
	v_and_b32_e32 v236, 0xffff0000, v236
	v_and_b32_e32 v237, 0xffff0000, v237
	v_add_f32_e32 v10, v10, v148
	v_add_f32_e32 v11, v11, v234
	v_add_f32_e32 v12, v12, v149
	v_add_f32_e32 v13, v13, v235
	v_add_f32_e32 v14, v14, v150
	v_add_f32_e32 v15, v15, v236
	v_add_f32_e32 v16, v16, v151
	v_add_f32_e32 v17, v17, v237
	v_cvt_pk_bf16_f32 v10, v10, v11
	v_cvt_pk_bf16_f32 v11, v12, v13
	v_cvt_pk_bf16_f32 v12, v14, v15
	v_cvt_pk_bf16_f32 v13, v16, v17
	global_store_dwordx4 v156, v[10:13], s[2:3]
	s_waitcnt vmcnt(15)
	v_lshlrev_b32_e32 v152, 16, v242
	v_lshlrev_b32_e32 v153, 16, v243
	v_lshlrev_b32_e32 v154, 16, v244
	v_lshlrev_b32_e32 v155, 16, v245
	v_and_b32_e32 v242, 0xffff0000, v242
	v_and_b32_e32 v243, 0xffff0000, v243
	v_and_b32_e32 v244, 0xffff0000, v244
	v_and_b32_e32 v245, 0xffff0000, v245
	v_add_f32_e32 v2, v2, v152
	v_add_f32_e32 v3, v3, v242
	v_add_f32_e32 v4, v4, v153
	v_add_f32_e32 v5, v5, v243
	v_add_f32_e32 v6, v6, v154
	v_add_f32_e32 v7, v7, v244
	v_add_f32_e32 v8, v8, v155
	v_add_f32_e32 v9, v9, v245
	v_cvt_pk_bf16_f32 v2, v2, v3
	v_cvt_pk_bf16_f32 v3, v4, v5
	v_cvt_pk_bf16_f32 v4, v6, v7
	v_cvt_pk_bf16_f32 v5, v8, v9
	global_store_dwordx4 v156, v[2:5], s[2:3] offset:256
	s_branch .LBB0_687
.Lg2_fast_f32:
	s_mov_b64 s[2:3], s[16:17]
	s_waitcnt vmcnt(15)
	v_lshlrev_b32_e32 v148, 16, v162
	v_lshlrev_b32_e32 v149, 16, v163
	v_lshlrev_b32_e32 v150, 16, v164
	v_lshlrev_b32_e32 v151, 16, v165
	v_and_b32_e32 v162, 0xffff0000, v162
	v_and_b32_e32 v163, 0xffff0000, v163
	v_and_b32_e32 v164, 0xffff0000, v164
	v_and_b32_e32 v165, 0xffff0000, v165
	v_add_f32_e32 v122, v122, v148
	v_add_f32_e32 v123, v123, v162
	v_add_f32_e32 v124, v124, v149
	v_add_f32_e32 v125, v125, v163
	v_add_f32_e32 v126, v126, v150
	v_add_f32_e32 v127, v127, v164
	v_add_f32_e32 v128, v128, v151
	v_add_f32_e32 v129, v129, v165
	global_store_dwordx4 v157, v[122:125], s[2:3]
	global_store_dwordx4 v157, v[126:129], s[2:3] offset:16
	s_waitcnt vmcnt(16)
	v_lshlrev_b32_e32 v152, 16, v166
	v_lshlrev_b32_e32 v153, 16, v167
	v_lshlrev_b32_e32 v154, 16, v168
	v_lshlrev_b32_e32 v155, 16, v169
	v_and_b32_e32 v166, 0xffff0000, v166
	v_and_b32_e32 v167, 0xffff0000, v167
	v_and_b32_e32 v168, 0xffff0000, v168
	v_and_b32_e32 v169, 0xffff0000, v169
	v_add_f32_e32 v114, v114, v152
	v_add_f32_e32 v115, v115, v166
	v_add_f32_e32 v116, v116, v153
	v_add_f32_e32 v117, v117, v167
	v_add_f32_e32 v118, v118, v154
	v_add_f32_e32 v119, v119, v168
	v_add_f32_e32 v120, v120, v155
	v_add_f32_e32 v121, v121, v169
	global_store_dwordx4 v157, v[114:117], s[2:3] offset:512
	global_store_dwordx4 v157, v[118:121], s[2:3] offset:528
	s_add_u32 s2, s2, 0x10000
	s_addc_u32 s3, s3, 0
	s_waitcnt vmcnt(17)
	v_lshlrev_b32_e32 v148, 16, v170
	v_lshlrev_b32_e32 v149, 16, v171
	v_lshlrev_b32_e32 v150, 16, v172
	v_lshlrev_b32_e32 v151, 16, v173
	v_and_b32_e32 v170, 0xffff0000, v170
	v_and_b32_e32 v171, 0xffff0000, v171
	v_and_b32_e32 v172, 0xffff0000, v172
	v_and_b32_e32 v173, 0xffff0000, v173
	v_add_f32_e32 v106, v106, v148
	v_add_f32_e32 v107, v107, v170
	v_add_f32_e32 v108, v108, v149
	v_add_f32_e32 v109, v109, v171
	v_add_f32_e32 v110, v110, v150
	v_add_f32_e32 v111, v111, v172
	v_add_f32_e32 v112, v112, v151
	v_add_f32_e32 v113, v113, v173
	global_store_dwordx4 v157, v[106:109], s[2:3]
	global_store_dwordx4 v157, v[110:113], s[2:3] offset:16
	s_waitcnt vmcnt(18)
	v_lshlrev_b32_e32 v152, 16, v174
	v_lshlrev_b32_e32 v153, 16, v175
	v_lshlrev_b32_e32 v154, 16, v176
	v_lshlrev_b32_e32 v155, 16, v177
	v_and_b32_e32 v174, 0xffff0000, v174
	v_and_b32_e32 v175, 0xffff0000, v175
	v_and_b32_e32 v176, 0xffff0000, v176
	v_and_b32_e32 v177, 0xffff0000, v177
	v_add_f32_e32 v98, v98, v152
	v_add_f32_e32 v99, v99, v174
	v_add_f32_e32 v100, v100, v153
	v_add_f32_e32 v101, v101, v175
	v_add_f32_e32 v102, v102, v154
	v_add_f32_e32 v103, v103, v176
	v_add_f32_e32 v104, v104, v155
	v_add_f32_e32 v105, v105, v177
	global_store_dwordx4 v157, v[98:101], s[2:3] offset:512
	global_store_dwordx4 v157, v[102:105], s[2:3] offset:528
	s_add_u32 s2, s2, 0x10000
	s_addc_u32 s3, s3, 0
	s_waitcnt vmcnt(19)
	v_lshlrev_b32_e32 v148, 16, v178
	v_lshlrev_b32_e32 v149, 16, v179
	v_lshlrev_b32_e32 v150, 16, v180
	v_lshlrev_b32_e32 v151, 16, v181
	v_and_b32_e32 v178, 0xffff0000, v178
	v_and_b32_e32 v179, 0xffff0000, v179
	v_and_b32_e32 v180, 0xffff0000, v180
	v_and_b32_e32 v181, 0xffff0000, v181
	v_add_f32_e32 v90, v90, v148
	v_add_f32_e32 v91, v91, v178
	v_add_f32_e32 v92, v92, v149
	v_add_f32_e32 v93, v93, v179
	v_add_f32_e32 v94, v94, v150
	v_add_f32_e32 v95, v95, v180
	v_add_f32_e32 v96, v96, v151
	v_add_f32_e32 v97, v97, v181
	global_store_dwordx4 v157, v[90:93], s[2:3]
	global_store_dwordx4 v157, v[94:97], s[2:3] offset:16
	s_waitcnt vmcnt(20)
;     __device__ __forceinline__ void operator()(const f32x4 (&acc)[2][2][4][2], const Unit& u, int wr, int wc, int fr, int fq) const {
;     ...
;             for (int m = 0; m < 4; ++m) { const size_t off = (size_t)(row0 + ai * HALF + m * 16) * ldc + col0;
; #pragma unroll
;                 for (int bj = 0; bj < 2; ++bj) { const size_t o = off + bj * HALF; f32x4 v0 = acc[ai][bj][m][0], v1 = acc[ai][bj][m][1];
;                     if (xin32) { v0 += *(const f32x4*)(xin32 + o); v1 += *(const f32x4*)(xin32 + o + 4); }
;                     else { const u32x4 rb = *(const u32x4*)(xinb + o);
;                         v0 += (f32x4){__uint_as_float(rb.x << 16), __uint_as_float(rb.x & 0xffff0000u), __uint_as_float(rb.y << 16), __uint_as_float(rb.y & 0xffff0000u)};
;                         v1 += (f32x4){__uint_as_float(rb.z << 16), __uint_as_float(rb.z & 0xffff0000u), __uint_as_float(rb.w << 16), __uint_as_float(rb.w & 0xffff0000u)}; }
;                     if (xout32) { *(f32x4*)(xout32 + o) = v0; *(f32x4*)(xout32 + o + 4) = v1; }
	v_lshlrev_b32_e32 v152, 16, v182
	v_lshlrev_b32_e32 v153, 16, v183
	v_lshlrev_b32_e32 v154, 16, v184
	v_lshlrev_b32_e32 v155, 16, v185
	v_and_b32_e32 v182, 0xffff0000, v182
	v_and_b32_e32 v183, 0xffff0000, v183
	v_and_b32_e32 v184, 0xffff0000, v184
	v_and_b32_e32 v185, 0xffff0000, v185
	v_add_f32_e32 v82, v82, v152
	v_add_f32_e32 v83, v83, v182
	v_add_f32_e32 v84, v84, v153
	v_add_f32_e32 v85, v85, v183
	v_add_f32_e32 v86, v86, v154
	v_add_f32_e32 v87, v87, v184
	v_add_f32_e32 v88, v88, v155
	v_add_f32_e32 v89, v89, v185
	global_store_dwordx4 v157, v[82:85], s[2:3] offset:512
	global_store_dwordx4 v157, v[86:89], s[2:3] offset:528
	s_add_u32 s2, s2, 0x10000
	s_addc_u32 s3, s3, 0
	s_waitcnt vmcnt(21)
	v_lshlrev_b32_e32 v148, 16, v202
	v_lshlrev_b32_e32 v149, 16, v203
	v_lshlrev_b32_e32 v150, 16, v204
	v_lshlrev_b32_e32 v151, 16, v205
	v_and_b32_e32 v202, 0xffff0000, v202
	v_and_b32_e32 v203, 0xffff0000, v203
	v_and_b32_e32 v204, 0xffff0000, v204
	v_and_b32_e32 v205, 0xffff0000, v205
	v_add_f32_e32 v74, v74, v148
	v_add_f32_e32 v75, v75, v202
	v_add_f32_e32 v76, v76, v149
	v_add_f32_e32 v77, v77, v203
	v_add_f32_e32 v78, v78, v150
	v_add_f32_e32 v79, v79, v204
	v_add_f32_e32 v80, v80, v151
	v_add_f32_e32 v81, v81, v205
	global_store_dwordx4 v157, v[74:77], s[2:3]
	global_store_dwordx4 v157, v[78:81], s[2:3] offset:16
	s_waitcnt vmcnt(22)
	v_lshlrev_b32_e32 v152, 16, v214
	v_lshlrev_b32_e32 v153, 16, v215
	v_lshlrev_b32_e32 v154, 16, v216
	v_lshlrev_b32_e32 v155, 16, v217
	v_and_b32_e32 v214, 0xffff0000, v214
	v_and_b32_e32 v215, 0xffff0000, v215
	v_and_b32_e32 v216, 0xffff0000, v216
	v_and_b32_e32 v217, 0xffff0000, v217
	v_add_f32_e32 v66, v66, v152
	v_add_f32_e32 v67, v67, v214
	v_add_f32_e32 v68, v68, v153
	v_add_f32_e32 v69, v69, v215
	v_add_f32_e32 v70, v70, v154
	v_add_f32_e32 v71, v71, v216
	v_add_f32_e32 v72, v72, v155
	v_add_f32_e32 v73, v73, v217
	global_store_dwordx4 v157, v[66:69], s[2:3] offset:512
	global_store_dwordx4 v157, v[70:73], s[2:3] offset:528
	s_add_u32 s2, s2, 0x50000
	s_addc_u32 s3, s3, 0
	s_waitcnt vmcnt(23)
	v_lshlrev_b32_e32 v148, 16, v218
	v_lshlrev_b32_e32 v149, 16, v219
	v_lshlrev_b32_e32 v150, 16, v220
	v_lshlrev_b32_e32 v151, 16, v221
	v_and_b32_e32 v218, 0xffff0000, v218
	v_and_b32_e32 v219, 0xffff0000, v219
	v_and_b32_e32 v220, 0xffff0000, v220
	v_and_b32_e32 v221, 0xffff0000, v221
	v_add_f32_e32 v58, v58, v148
	v_add_f32_e32 v59, v59, v218
	v_add_f32_e32 v60, v60, v149
	v_add_f32_e32 v61, v61, v219
	v_add_f32_e32 v62, v62, v150
	v_add_f32_e32 v63, v63, v220
	v_add_f32_e32 v64, v64, v151
	v_add_f32_e32 v65, v65, v221
	global_store_dwordx4 v157, v[58:61], s[2:3]
	global_store_dwordx4 v157, v[62:65], s[2:3] offset:16
	s_waitcnt vmcnt(24)
	v_lshlrev_b32_e32 v152, 16, v222
	v_lshlrev_b32_e32 v153, 16, v223
	v_lshlrev_b32_e32 v154, 16, v224
	v_lshlrev_b32_e32 v155, 16, v225
	v_and_b32_e32 v222, 0xffff0000, v222
	v_and_b32_e32 v223, 0xffff0000, v223
	v_and_b32_e32 v224, 0xffff0000, v224
	v_and_b32_e32 v225, 0xffff0000, v225
	v_add_f32_e32 v50, v50, v152
	v_add_f32_e32 v51, v51, v222
	v_add_f32_e32 v52, v52, v153
	v_add_f32_e32 v53, v53, v223
	v_add_f32_e32 v54, v54, v154
	v_add_f32_e32 v55, v55, v224
	v_add_f32_e32 v56, v56, v155
	v_add_f32_e32 v57, v57, v225
	global_store_dwordx4 v157, v[50:53], s[2:3] offset:512
	global_store_dwordx4 v157, v[54:57], s[2:3] offset:528
	s_add_u32 s2, s2, 0x10000
	s_addc_u32 s3, s3, 0
	s_waitcnt vmcnt(25)
;     __device__ __forceinline__ void operator()(const f32x4 (&acc)[2][2][4][2], const Unit& u, int wr, int wc, int fr, int fq) const {
;     ...
;             for (int m = 0; m < 4; ++m) { const size_t off = (size_t)(row0 + ai * HALF + m * 16) * ldc + col0;
; #pragma unroll
;                 for (int bj = 0; bj < 2; ++bj) { const size_t o = off + bj * HALF; f32x4 v0 = acc[ai][bj][m][0], v1 = acc[ai][bj][m][1];
;                     if (xin32) { v0 += *(const f32x4*)(xin32 + o); v1 += *(const f32x4*)(xin32 + o + 4); }
;                     else { const u32x4 rb = *(const u32x4*)(xinb + o);
;                         v0 += (f32x4){__uint_as_float(rb.x << 16), __uint_as_float(rb.x & 0xffff0000u), __uint_as_float(rb.y << 16), __uint_as_float(rb.y & 0xffff0000u)};
;                         v1 += (f32x4){__uint_as_float(rb.z << 16), __uint_as_float(rb.z & 0xffff0000u), __uint_as_float(rb.w << 16), __uint_as_float(rb.w & 0xffff0000u)}; }
;                     if (xout32) { *(f32x4*)(xout32 + o) = v0; *(f32x4*)(xout32 + o + 4) = v1; }
	v_lshlrev_b32_e32 v148, 16, v226
	v_lshlrev_b32_e32 v149, 16, v227
	v_lshlrev_b32_e32 v150, 16, v228
	v_lshlrev_b32_e32 v151, 16, v229
	v_and_b32_e32 v226, 0xffff0000, v226
	v_and_b32_e32 v227, 0xffff0000, v227
	v_and_b32_e32 v228, 0xffff0000, v228
	v_and_b32_e32 v229, 0xffff0000, v229
	v_add_f32_e32 v42, v42, v148
	v_add_f32_e32 v43, v43, v226
	v_add_f32_e32 v44, v44, v149
	v_add_f32_e32 v45, v45, v227
	v_add_f32_e32 v46, v46, v150
	v_add_f32_e32 v47, v47, v228
	v_add_f32_e32 v48, v48, v151
	v_add_f32_e32 v49, v49, v229
	global_store_dwordx4 v157, v[42:45], s[2:3]
	global_store_dwordx4 v157, v[46:49], s[2:3] offset:16
	s_waitcnt vmcnt(26)
	v_lshlrev_b32_e32 v152, 16, v230
	v_lshlrev_b32_e32 v153, 16, v231
	v_lshlrev_b32_e32 v154, 16, v232
	v_lshlrev_b32_e32 v155, 16, v233
	v_and_b32_e32 v230, 0xffff0000, v230
	v_and_b32_e32 v231, 0xffff0000, v231
	v_and_b32_e32 v232, 0xffff0000, v232
	v_and_b32_e32 v233, 0xffff0000, v233
	v_add_f32_e32 v34, v34, v152
	v_add_f32_e32 v35, v35, v230
	v_add_f32_e32 v36, v36, v153
	v_add_f32_e32 v37, v37, v231
	v_add_f32_e32 v38, v38, v154
	v_add_f32_e32 v39, v39, v232
	v_add_f32_e32 v40, v40, v155
	v_add_f32_e32 v41, v41, v233
	global_store_dwordx4 v157, v[34:37], s[2:3] offset:512
	global_store_dwordx4 v157, v[38:41], s[2:3] offset:528
	s_add_u32 s2, s2, 0x10000
	s_addc_u32 s3, s3, 0
	s_waitcnt vmcnt(27)
	v_lshlrev_b32_e32 v148, 16, v130
	v_lshlrev_b32_e32 v149, 16, v131
	v_lshlrev_b32_e32 v150, 16, v132
	v_lshlrev_b32_e32 v151, 16, v133
	v_and_b32_e32 v130, 0xffff0000, v130
	v_and_b32_e32 v131, 0xffff0000, v131
	v_and_b32_e32 v132, 0xffff0000, v132
	v_and_b32_e32 v133, 0xffff0000, v133
	v_add_f32_e32 v26, v26, v148
	v_add_f32_e32 v27, v27, v130
	v_add_f32_e32 v28, v28, v149
	v_add_f32_e32 v29, v29, v131
	v_add_f32_e32 v30, v30, v150
	v_add_f32_e32 v31, v31, v132
	v_add_f32_e32 v32, v32, v151
	v_add_f32_e32 v33, v33, v133
	global_store_dwordx4 v157, v[26:29], s[2:3]
	global_store_dwordx4 v157, v[30:33], s[2:3] offset:16
	s_waitcnt vmcnt(28)
	v_lshlrev_b32_e32 v152, 16, v134
	v_lshlrev_b32_e32 v153, 16, v135
	v_lshlrev_b32_e32 v154, 16, v136
	v_lshlrev_b32_e32 v155, 16, v137
	v_and_b32_e32 v134, 0xffff0000, v134
	v_and_b32_e32 v135, 0xffff0000, v135
	v_and_b32_e32 v136, 0xffff0000, v136
	v_and_b32_e32 v137, 0xffff0000, v137
	v_add_f32_e32 v18, v18, v152
	v_add_f32_e32 v19, v19, v134
	v_add_f32_e32 v20, v20, v153
	v_add_f32_e32 v21, v21, v135
	v_add_f32_e32 v22, v22, v154
	v_add_f32_e32 v23, v23, v136
	v_add_f32_e32 v24, v24, v155
	v_add_f32_e32 v25, v25, v137
	global_store_dwordx4 v157, v[18:21], s[2:3] offset:512
	global_store_dwordx4 v157, v[22:25], s[2:3] offset:528
	s_add_u32 s2, s2, 0x10000
	s_addc_u32 s3, s3, 0
	s_waitcnt vmcnt(29)
	v_lshlrev_b32_e32 v148, 16, v234
	v_lshlrev_b32_e32 v149, 16, v235
	v_lshlrev_b32_e32 v150, 16, v236
	v_lshlrev_b32_e32 v151, 16, v237
	v_and_b32_e32 v234, 0xffff0000, v234
	v_and_b32_e32 v235, 0xffff0000, v235
	v_and_b32_e32 v236, 0xffff0000, v236
	v_and_b32_e32 v237, 0xffff0000, v237
	v_add_f32_e32 v10, v10, v148
	v_add_f32_e32 v11, v11, v234
	v_add_f32_e32 v12, v12, v149
	v_add_f32_e32 v13, v13, v235
	v_add_f32_e32 v14, v14, v150
	v_add_f32_e32 v15, v15, v236
	v_add_f32_e32 v16, v16, v151
	v_add_f32_e32 v17, v17, v237
	global_store_dwordx4 v157, v[10:13], s[2:3]
	global_store_dwordx4 v157, v[14:17], s[2:3] offset:16
	s_waitcnt vmcnt(30)
	v_lshlrev_b32_e32 v152, 16, v242
	v_lshlrev_b32_e32 v153, 16, v243
	v_lshlrev_b32_e32 v154, 16, v244
	v_lshlrev_b32_e32 v155, 16, v245
	v_and_b32_e32 v242, 0xffff0000, v242
	v_and_b32_e32 v243, 0xffff0000, v243
	v_and_b32_e32 v244, 0xffff0000, v244
	v_and_b32_e32 v245, 0xffff0000, v245
	v_add_f32_e32 v2, v2, v152
	v_add_f32_e32 v3, v3, v242
	v_add_f32_e32 v4, v4, v153
	v_add_f32_e32 v5, v5, v243
	v_add_f32_e32 v6, v6, v154
	v_add_f32_e32 v7, v7, v244
	v_add_f32_e32 v8, v8, v155
	v_add_f32_e32 v9, v9, v245
	global_store_dwordx4 v157, v[2:5], s[2:3] offset:512
	global_store_dwordx4 v157, v[6:9], s[2:3] offset:528
	s_branch .LBB0_687
